# v114 + GEMM1 work split: upper grid half (which skips GEMM2) takes the lower half's 4th GEMM1 round as a 5th round
# baseline (speedup 1.0000x reference)
; template <int GI>
; __device__ __forceinline__ bool sched_next(unsigned char* ws, int i, int G, int c, GUnit& u) {
;     ...
;     const int L = i * G + c;
;     u.SA = 128 * d.ldc; u.SR = d.ldc; u.SB = 128; u.SX = 64; u.scale = d.scale;
;     if (d.kind == 0) {
;         constexpr int nwg = d.nM * d.nN;
;         if (L >= nwg) return false;
;         int wgid = L;
;         { constexpr int q = nwg / 8, r = nwg % 8; const int xcd = wgid % 8, off = wgid / 8; wgid = (xcd < r ? xcd * (q + 1) : r * (q + 1) + (xcd - r) * q) + off; }
; template <int GI>
; __device__ __forceinline__ void gemm_phase(LAS unsigned char* lds, unsigned char* ws, int G, int cblk) {
;     ...
;         const bool has_next = sched_next<GI>(ws, ui + 1, G, cblk, nxt);
.LBB0_116:
	s_add_i32 s27, s27, 1
	s_mul_i32 s14, s27, s30
	s_add_i32 s14, s14, s2
	s_cmpk_lg_u32 s30, 0x100
	s_cbranch_scc1 .Lg1r_done
	s_cmpk_lt_u32 s2, 0x80
	s_cbranch_scc0 .Lg1r_upper
	s_cmpk_lt_u32 s14, 0x300
	s_cbranch_scc1 .Lg1r_done
	s_movk_i32 s14, 0x400
	s_branch .Lg1r_done
.Lg1r_upper:
	s_cmpk_lt_u32 s14, 0x400
	s_cbranch_scc1 .Lg1r_done
	s_cmpk_lt_u32 s14, 0x500
	s_cbranch_scc0 .Lg1r_done
	s_sub_i32 s14, s14, 0x180
.Lg1r_done:
	s_cmpk_lt_i32 s14, 0x400
	s_cselect_b64 s[70:71], -1, 0
	s_cmpk_gt_i32 s14, 0x3ff
	s_cbranch_scc1 .LBB0_122
	s_ashr_i32 s4, s14, 31
	s_lshr_b32 s4, s4, 29
	s_add_i32 s4, s14, s4
	s_and_b32 s15, s4, -8
	s_sub_i32 s34, s14, s15
	s_cmp_gt_i32 s34, -1
	s_mov_b64 s[14:15], -1
	s_cbranch_scc0 .LBB0_119
	s_lshl_b32 s35, s34, 7
	s_mov_b64 s[14:15], 0
